# P3 retention out-proj gated-add epilogue: gate+MG loads pipelined 8 groups ahead, counted vmcnt (on top of P7 residual epilogue)
# speedup vs baseline: 1.0147x; 1.0084x over previous
; #define PG8_STAGE(bufoff, gbase, voff) do { _Pragma("unroll") for (int _i = 0; _i < 2; ++_i) \
;         __builtin_amdgcn_global_load_lds((const unsigned*)((const char*)(gbase) + (voff)[_i]), (PG8_LAS unsigned*)(lds + (bufoff) + ldsw + _i * 8192), 16, 0, 0); } while (0)
; #define PG8_LDA(dst, b, h) do { _Pragma("unroll") for (int m = 0; m < 4; ++m) _Pragma("unroll") for (int k = 0; k < 2; ++k) dst[m][k] = *(const PG8_LAS bf16x8*)(lds + PG8_SA(b, h) + aoff + m * 2048 + k * 1024); } while (0)
; #define PG8_LDB(dst, b, h) do { _Pragma("unroll") for (int n = 0; n < 2; ++n) _Pragma("unroll") for (int k = 0; k < 2; ++k) dst[n][k] = *(const PG8_LAS bf16x8*)(lds + PG8_SB(b, h) + boff + n * 2048 + k * 1024); } while (0)
; #define PG8_MMA(ai, bj, At, Bt) do { __builtin_amdgcn_s_setprio(1); _Pragma("unroll") for (int m = 0; m < 4; ++m) _Pragma("unroll") for (int n = 0; n < 2; ++n) _Pragma("unroll") for (int k = 0; k < 2; ++k) \
;         acc[ai][bj][m][n] = __builtin_amdgcn_mfma_f32_16x16x32_bf16(Bt[n][k], At[m][k], acc[ai][bj][m][n], 0, 0, 0); __builtin_amdgcn_s_setprio(0); } while (0)
; #define PG8_WAIT_V(n) asm volatile("s_waitcnt vmcnt(" #n ")" ::: "memory")
; #define PG8_BAR __builtin_amdgcn_s_barrier()
; template <class Epi, class Sched, bool ALIGN_EPI = false, bool SP2 = false>
; __device__ __forceinline__ void gemm_phase(PG8_LAS unsigned char* lds, const Gemm g, const Sched& S, const Epi& E) {
;     ...
;         for (int t = 0; t < nt; t += 2) {
;             const bool last = (t == nt - 2);
;             const char* a1 = cA + (size_t)(t + 1) * kstep;
;             const char* a2 = last ? nA : cA + (size_t)(t + 2) * kstep; const char* b2 = last ? nB : cB + (size_t)(t + 2) * kstep;
;             const char* a3 = a2 + kstep; const char* b3 = b2 + kstep;
;             if (last && has_next) S.a_ready(nxt);
;             if constexpr (SP2) {
;             PG8_LDB(B0, 0, 0); PG8_LDB(B1, 0, 1); PG8_SCHED; PG8_LDA(At, 0, 0); PG8_STAGE(PG8_SA(1, 1), a1 + hstep, voffA);
;             PG8_WAIT_V(8); PG8_WAIT_L(0); PG8_BAR; PG8_MMA(0, 0, At, B0); PG8_MMA(0, 1, At, B1); PG8_BAR; PG8_SCHED;
;             PG8_LDA(At, 0, 1); PG8_STAGE(PG8_SB(0, 0), b2, voffB); PG8_STAGE(PG8_SB(0, 1), b2 + hstep, voffB); PG8_STAGE(PG8_SA(0, 0), a2, voffA);
;             PG8_WAIT_V(8); PG8_WAIT_L(0); PG8_BAR; PG8_MMA(1, 0, At, B0); PG8_MMA(1, 1, At, B1); PG8_BAR; PG8_SCHED;
.LBB0_725:
	s_add_u32 s20, s18, 0xfffc0080
	s_addc_u32 s21, s19, -1
	s_add_i32 s40, 0, 0x10000
	s_cmp_eq_u32 s39, 12
	s_cselect_b32 s23, s9, s21
	s_cselect_b32 s22, s15, s20
	v_add_u32_e32 v144, s40, v147
	s_cselect_b32 s21, s7, s38
	s_cselect_b32 s20, s17, s33
	s_add_i32 s42, 0, 0x14000
	ds_read_b128 v[140:143], v144
	ds_read_b128 v[150:153], v144 offset:1024
	ds_read_b128 v[154:157], v144 offset:2048
	ds_read_b128 v[158:161], v144 offset:3072
	v_add_u32_e32 v144, s42, v147
	ds_read_b128 v[162:165], v144
	ds_read_b128 v[166:169], v144 offset:1024
	ds_read_b128 v[170:173], v144 offset:2048
	ds_read_b128 v[174:177], v144 offset:3072
	v_lshl_add_u64 v[144:145], s[18:19], 0, v[136:137]
	s_add_i32 m0, s28, 0xc000
	ds_read_b128 v[178:181], v148
	ds_read_b128 v[182:185], v148 offset:1024
	ds_read_b128 v[194:197], v148 offset:2048
	ds_read_b128 v[198:201], v148 offset:3072
	ds_read_b128 v[202:205], v148 offset:4096
	ds_read_b128 v[210:213], v148 offset:5120
	ds_read_b128 v[214:217], v148 offset:6144
	ds_read_b128 v[218:221], v148 offset:7168
	global_load_lds_dwordx4 v[144:145], off
	v_lshl_add_u64 v[144:145], s[18:19], 0, v[138:139]
	s_add_i32 m0, s28, 0xe000
	s_nop 0
	global_load_lds_dwordx4 v[144:145], off
	s_waitcnt vmcnt(8)
	s_waitcnt lgkmcnt(0)
	s_barrier
	s_setprio 1
	s_waitcnt lgkmcnt(0)
	v_mfma_f32_16x16x32_bf16 v[124:127], v[140:143], v[178:181], v[124:127]
	v_mfma_f32_16x16x32_bf16 v[120:123], v[154:157], v[178:181], v[120:123]
	v_mfma_f32_16x16x32_bf16 v[108:111], v[140:143], v[194:197], v[108:111]
	v_mfma_f32_16x16x32_bf16 v[104:107], v[154:157], v[194:197], v[104:107]
	v_mfma_f32_16x16x32_bf16 v[92:95], v[140:143], v[202:205], v[92:95]
	v_mfma_f32_16x16x32_bf16 v[88:91], v[154:157], v[202:205], v[88:91]
	v_mfma_f32_16x16x32_bf16 v[76:79], v[140:143], v[214:217], v[76:79]
	v_mfma_f32_16x16x32_bf16 v[72:75], v[154:157], v[214:217], v[72:75]
	v_mfma_f32_16x16x32_bf16 v[124:127], v[150:153], v[182:185], v[124:127]
	v_mfma_f32_16x16x32_bf16 v[120:123], v[158:161], v[182:185], v[120:123]
	v_mfma_f32_16x16x32_bf16 v[108:111], v[150:153], v[198:201], v[108:111]
	v_mfma_f32_16x16x32_bf16 v[104:107], v[158:161], v[198:201], v[104:107]
	v_mfma_f32_16x16x32_bf16 v[92:95], v[150:153], v[210:213], v[92:95]
	v_mfma_f32_16x16x32_bf16 v[88:91], v[158:161], v[210:213], v[88:91]
	v_mfma_f32_16x16x32_bf16 v[76:79], v[150:153], v[218:221], v[76:79]
	v_mfma_f32_16x16x32_bf16 v[72:75], v[158:161], v[218:221], v[72:75]
	s_setprio 0
	s_setprio 1
	v_mfma_f32_16x16x32_bf16 v[116:119], v[162:165], v[178:181], v[116:119]
	v_mfma_f32_16x16x32_bf16 v[112:115], v[170:173], v[178:181], v[112:115]
	v_mfma_f32_16x16x32_bf16 v[100:103], v[162:165], v[194:197], v[100:103]
	v_mfma_f32_16x16x32_bf16 v[96:99], v[170:173], v[194:197], v[96:99]
	v_mfma_f32_16x16x32_bf16 v[84:87], v[162:165], v[202:205], v[84:87]
	v_mfma_f32_16x16x32_bf16 v[80:83], v[170:173], v[202:205], v[80:83]
	v_mfma_f32_16x16x32_bf16 v[68:71], v[162:165], v[214:217], v[68:71]
	v_mfma_f32_16x16x32_bf16 v[64:67], v[170:173], v[214:217], v[64:67]
	v_mfma_f32_16x16x32_bf16 v[116:119], v[166:169], v[182:185], v[116:119]
	v_mfma_f32_16x16x32_bf16 v[112:115], v[174:177], v[182:185], v[112:115]
	v_mfma_f32_16x16x32_bf16 v[100:103], v[166:169], v[198:201], v[100:103]
	v_mfma_f32_16x16x32_bf16 v[96:99], v[174:177], v[198:201], v[96:99]
	v_mfma_f32_16x16x32_bf16 v[84:87], v[166:169], v[210:213], v[84:87]
	v_mfma_f32_16x16x32_bf16 v[80:83], v[174:177], v[210:213], v[80:83]
	v_mfma_f32_16x16x32_bf16 v[68:71], v[166:169], v[218:221], v[68:71]
	v_mfma_f32_16x16x32_bf16 v[64:67], v[174:177], v[218:221], v[64:67]
	s_setprio 0
	s_barrier
	s_add_i32 s40, s40, s27
	v_lshl_add_u64 v[144:145], s[20:21], 0, v[188:189]
	s_mov_b32 m0, s40
	ds_read_b128 v[178:181], v148 offset:16384
	ds_read_b128 v[182:185], v148 offset:17408
	ds_read_b128 v[194:197], v148 offset:18432
	ds_read_b128 v[198:201], v148 offset:19456
	ds_read_b128 v[202:205], v148 offset:20480
	ds_read_b128 v[210:213], v148 offset:21504
	ds_read_b128 v[214:217], v148 offset:22528
	ds_read_b128 v[218:221], v148 offset:23552
	global_load_lds_dwordx4 v[144:145], off
	s_add_i32 m0, s40, 0x2000
	s_add_u32 s40, s20, 0x40000
	v_lshl_add_u64 v[186:187], s[20:21], 0, v[132:133]
	s_addc_u32 s41, s21, 0
	s_add_i32 s42, s42, s27
	global_load_lds_dwordx4 v[186:187], off
	v_lshl_add_u64 v[190:191], s[40:41], 0, v[188:189]
	s_mov_b32 m0, s42
	v_lshl_add_u64 v[222:223], s[22:23], 0, v[130:131]
	global_load_lds_dwordx4 v[190:191], off
	v_lshl_add_u64 v[190:191], s[40:41], 0, v[132:133]
	s_add_i32 m0, s42, 0x2000
	s_nop 0
	global_load_lds_dwordx4 v[190:191], off
	v_lshl_add_u64 v[190:191], s[22:23], 0, v[128:129]
	s_mov_b32 m0, s28
	s_nop 0
	global_load_lds_dwordx4 v[190:191], off
	s_mov_b32 m0, s29
	s_nop 0
	global_load_lds_dwordx4 v[222:223], off
	s_waitcnt vmcnt(8)
	s_waitcnt lgkmcnt(0)
	s_barrier
; #define PG8_STAGE(bufoff, gbase, voff) do { _Pragma("unroll") for (int _i = 0; _i < 2; ++_i) \
;         __builtin_amdgcn_global_load_lds((const unsigned*)((const char*)(gbase) + (voff)[_i]), (PG8_LAS unsigned*)(lds + (bufoff) + ldsw + _i * 8192), 16, 0, 0); } while (0)
; #define PG8_LDA(dst, b, h) do { _Pragma("unroll") for (int m = 0; m < 4; ++m) _Pragma("unroll") for (int k = 0; k < 2; ++k) dst[m][k] = *(const PG8_LAS bf16x8*)(lds + PG8_SA(b, h) + aoff + m * 2048 + k * 1024); } while (0)
; #define PG8_LDB(dst, b, h) do { _Pragma("unroll") for (int n = 0; n < 2; ++n) _Pragma("unroll") for (int k = 0; k < 2; ++k) dst[n][k] = *(const PG8_LAS bf16x8*)(lds + PG8_SB(b, h) + boff + n * 2048 + k * 1024); } while (0)
; #define PG8_MMA(ai, bj, At, Bt) do { __builtin_amdgcn_s_setprio(1); _Pragma("unroll") for (int m = 0; m < 4; ++m) _Pragma("unroll") for (int n = 0; n < 2; ++n) _Pragma("unroll") for (int k = 0; k < 2; ++k) \
;         acc[ai][bj][m][n] = __builtin_amdgcn_mfma_f32_16x16x32_bf16(Bt[n][k], At[m][k], acc[ai][bj][m][n], 0, 0, 0); __builtin_amdgcn_s_setprio(0); } while (0)
; #define PG8_WAIT_V(n) asm volatile("s_waitcnt vmcnt(" #n ")" ::: "memory")
; #define PG8_WAIT_L(n) asm volatile("s_waitcnt lgkmcnt(" #n ")" ::: "memory")
; #define PG8_BAR __builtin_amdgcn_s_barrier()
; #define PG8_SCHED __builtin_amdgcn_sched_barrier(0)
; template <class Epi, class Sched, bool ALIGN_EPI = false, bool SP2 = false>
; __device__ __forceinline__ void gemm_phase(PG8_LAS unsigned char* lds, const Gemm g, const Sched& S, const Epi& E) {
;     ...
;             PG8_WAIT_V(8); PG8_WAIT_L(0); PG8_BAR; PG8_MMA(1, 0, At, B0); PG8_MMA(1, 1, At, B1); PG8_BAR; PG8_SCHED;
;             PG8_LDB(B0, 1, 0); PG8_LDB(B1, 1, 1); PG8_SCHED; PG8_LDA(At, 1, 0); PG8_STAGE(PG8_SA(0, 1), a2 + hstep, voffA);
;             PG8_WAIT_V(8); PG8_WAIT_L(0); PG8_BAR; PG8_MMA(0, 0, At, B0); PG8_MMA(0, 1, At, B1); PG8_BAR; PG8_SCHED;
;             PG8_LDA(At, 1, 1); PG8_STAGE(PG8_SB(1, 0), b3, voffB); PG8_STAGE(PG8_SB(1, 1), b3 + hstep, voffB); PG8_STAGE(PG8_SA(1, 0), a3, voffA);
;             PG8_WAIT_V(8); PG8_WAIT_L(0); PG8_BAR; PG8_MMA(1, 0, At, B0); PG8_MMA(1, 1, At, B1); PG8_BAR; PG8_SCHED;
	s_setprio 1
	s_waitcnt lgkmcnt(0)
	v_mfma_f32_16x16x32_bf16 v[60:63], v[140:143], v[178:181], v[60:63]
	v_mfma_f32_16x16x32_bf16 v[56:59], v[154:157], v[178:181], v[56:59]
	v_mfma_f32_16x16x32_bf16 v[44:47], v[140:143], v[194:197], v[44:47]
	v_mfma_f32_16x16x32_bf16 v[40:43], v[154:157], v[194:197], v[40:43]
	v_mfma_f32_16x16x32_bf16 v[28:31], v[140:143], v[202:205], v[28:31]
	v_mfma_f32_16x16x32_bf16 v[24:27], v[154:157], v[202:205], v[24:27]
	v_mfma_f32_16x16x32_bf16 v[12:15], v[140:143], v[214:217], v[12:15]
	v_mfma_f32_16x16x32_bf16 v[8:11], v[154:157], v[214:217], v[8:11]
	v_mfma_f32_16x16x32_bf16 v[60:63], v[150:153], v[182:185], v[60:63]
	v_mfma_f32_16x16x32_bf16 v[56:59], v[158:161], v[182:185], v[56:59]
	v_mfma_f32_16x16x32_bf16 v[44:47], v[150:153], v[198:201], v[44:47]
	v_mfma_f32_16x16x32_bf16 v[40:43], v[158:161], v[198:201], v[40:43]
	v_mfma_f32_16x16x32_bf16 v[28:31], v[150:153], v[210:213], v[28:31]
	v_mfma_f32_16x16x32_bf16 v[24:27], v[158:161], v[210:213], v[24:27]
	v_mfma_f32_16x16x32_bf16 v[12:15], v[150:153], v[218:221], v[12:15]
	v_mfma_f32_16x16x32_bf16 v[8:11], v[158:161], v[218:221], v[8:11]
	s_setprio 0
	s_setprio 1
	v_mfma_f32_16x16x32_bf16 v[52:55], v[162:165], v[178:181], v[52:55]
	v_mfma_f32_16x16x32_bf16 v[48:51], v[170:173], v[178:181], v[48:51]
	v_mfma_f32_16x16x32_bf16 v[36:39], v[162:165], v[194:197], v[36:39]
	v_mfma_f32_16x16x32_bf16 v[32:35], v[170:173], v[194:197], v[32:35]
	v_mfma_f32_16x16x32_bf16 v[20:23], v[162:165], v[202:205], v[20:23]
	v_mfma_f32_16x16x32_bf16 v[16:19], v[170:173], v[202:205], v[16:19]
	v_mfma_f32_16x16x32_bf16 v[4:7], v[162:165], v[214:217], v[4:7]
	v_mfma_f32_16x16x32_bf16 v[0:3], v[170:173], v[214:217], v[0:3]
	v_mfma_f32_16x16x32_bf16 v[52:55], v[166:169], v[182:185], v[52:55]
	v_mfma_f32_16x16x32_bf16 v[48:51], v[174:177], v[182:185], v[48:51]
	v_mfma_f32_16x16x32_bf16 v[36:39], v[166:169], v[198:201], v[36:39]
	v_mfma_f32_16x16x32_bf16 v[32:35], v[174:177], v[198:201], v[32:35]
	v_mfma_f32_16x16x32_bf16 v[20:23], v[166:169], v[210:213], v[20:23]
	v_mfma_f32_16x16x32_bf16 v[16:19], v[174:177], v[210:213], v[16:19]
	v_mfma_f32_16x16x32_bf16 v[4:7], v[166:169], v[218:221], v[4:7]
	v_mfma_f32_16x16x32_bf16 v[0:3], v[174:177], v[218:221], v[0:3]
	s_setprio 0
	s_barrier
	s_add_i32 s40, 0, 0x18000
	v_add_u32_e32 v149, s40, v147
	s_add_i32 s41, 0, 0x1c000
	ds_read_b128 v[140:143], v149
	ds_read_b128 v[150:153], v149 offset:1024
	ds_read_b128 v[154:157], v149 offset:2048
	ds_read_b128 v[158:161], v149 offset:3072
	v_add_u32_e32 v149, s41, v147
	ds_read_b128 v[162:165], v149
	ds_read_b128 v[166:169], v149 offset:1024
	ds_read_b128 v[170:173], v149 offset:2048
	ds_read_b128 v[174:177], v149 offset:3072
	s_add_u32 s22, s22, 0x40000
	s_addc_u32 s23, s23, 0
	s_mov_b32 m0, s30
	v_lshl_add_u64 v[224:225], s[22:23], 0, v[128:129]
	ds_read_b128 v[178:181], v148 offset:32768
	ds_read_b128 v[182:185], v148 offset:33792
	ds_read_b128 v[194:197], v148 offset:34816
	ds_read_b128 v[198:201], v148 offset:35840
	ds_read_b128 v[202:205], v148 offset:36864
	ds_read_b128 v[210:213], v148 offset:37888
	ds_read_b128 v[214:217], v148 offset:38912
	ds_read_b128 v[218:221], v148 offset:39936
	global_load_lds_dwordx4 v[224:225], off
	v_lshl_add_u64 v[224:225], s[22:23], 0, v[130:131]
	s_mov_b32 m0, s31
	s_nop 0
	global_load_lds_dwordx4 v[224:225], off
	s_waitcnt vmcnt(8)
	s_waitcnt lgkmcnt(0)
	s_barrier
	s_setprio 1
	s_waitcnt lgkmcnt(0)
	v_mfma_f32_16x16x32_bf16 v[124:127], v[140:143], v[178:181], v[124:127]
	v_mfma_f32_16x16x32_bf16 v[120:123], v[154:157], v[178:181], v[120:123]
	v_mfma_f32_16x16x32_bf16 v[108:111], v[140:143], v[194:197], v[108:111]
	v_mfma_f32_16x16x32_bf16 v[104:107], v[154:157], v[194:197], v[104:107]
	v_mfma_f32_16x16x32_bf16 v[92:95], v[140:143], v[202:205], v[92:95]
	v_mfma_f32_16x16x32_bf16 v[88:91], v[154:157], v[202:205], v[88:91]
	v_mfma_f32_16x16x32_bf16 v[76:79], v[140:143], v[214:217], v[76:79]
	v_mfma_f32_16x16x32_bf16 v[72:75], v[154:157], v[214:217], v[72:75]
	v_mfma_f32_16x16x32_bf16 v[124:127], v[150:153], v[182:185], v[124:127]
	v_mfma_f32_16x16x32_bf16 v[120:123], v[158:161], v[182:185], v[120:123]
	v_mfma_f32_16x16x32_bf16 v[108:111], v[150:153], v[198:201], v[108:111]
	v_mfma_f32_16x16x32_bf16 v[104:107], v[158:161], v[198:201], v[104:107]
	v_mfma_f32_16x16x32_bf16 v[92:95], v[150:153], v[210:213], v[92:95]
	v_mfma_f32_16x16x32_bf16 v[88:91], v[158:161], v[210:213], v[88:91]
	v_mfma_f32_16x16x32_bf16 v[76:79], v[150:153], v[218:221], v[76:79]
	v_mfma_f32_16x16x32_bf16 v[72:75], v[158:161], v[218:221], v[72:75]
	s_setprio 0
	s_setprio 1
	v_mfma_f32_16x16x32_bf16 v[116:119], v[162:165], v[178:181], v[116:119]
	v_mfma_f32_16x16x32_bf16 v[112:115], v[170:173], v[178:181], v[112:115]
	v_mfma_f32_16x16x32_bf16 v[100:103], v[162:165], v[194:197], v[100:103]
	v_mfma_f32_16x16x32_bf16 v[96:99], v[170:173], v[194:197], v[96:99]
	v_mfma_f32_16x16x32_bf16 v[84:87], v[162:165], v[202:205], v[84:87]
	v_mfma_f32_16x16x32_bf16 v[80:83], v[170:173], v[202:205], v[80:83]
	v_mfma_f32_16x16x32_bf16 v[68:71], v[162:165], v[214:217], v[68:71]
	v_mfma_f32_16x16x32_bf16 v[64:67], v[170:173], v[214:217], v[64:67]
	v_mfma_f32_16x16x32_bf16 v[116:119], v[166:169], v[182:185], v[116:119]
	v_mfma_f32_16x16x32_bf16 v[112:115], v[174:177], v[182:185], v[112:115]
	v_mfma_f32_16x16x32_bf16 v[100:103], v[166:169], v[198:201], v[100:103]
	v_mfma_f32_16x16x32_bf16 v[96:99], v[174:177], v[198:201], v[96:99]
	v_mfma_f32_16x16x32_bf16 v[84:87], v[166:169], v[210:213], v[84:87]
	v_mfma_f32_16x16x32_bf16 v[80:83], v[174:177], v[210:213], v[80:83]
	v_mfma_f32_16x16x32_bf16 v[68:71], v[166:169], v[218:221], v[68:71]
	v_mfma_f32_16x16x32_bf16 v[64:67], v[174:177], v[218:221], v[64:67]
	s_setprio 0
	s_barrier
; #define PG8_STAGE(bufoff, gbase, voff) do { _Pragma("unroll") for (int _i = 0; _i < 2; ++_i) \
;         __builtin_amdgcn_global_load_lds((const unsigned*)((const char*)(gbase) + (voff)[_i]), (PG8_LAS unsigned*)(lds + (bufoff) + ldsw + _i * 8192), 16, 0, 0); } while (0)
; #define PG8_LDA(dst, b, h) do { _Pragma("unroll") for (int m = 0; m < 4; ++m) _Pragma("unroll") for (int k = 0; k < 2; ++k) dst[m][k] = *(const PG8_LAS bf16x8*)(lds + PG8_SA(b, h) + aoff + m * 2048 + k * 1024); } while (0)
; #define PG8_MMA(ai, bj, At, Bt) do { __builtin_amdgcn_s_setprio(1); _Pragma("unroll") for (int m = 0; m < 4; ++m) _Pragma("unroll") for (int n = 0; n < 2; ++n) _Pragma("unroll") for (int k = 0; k < 2; ++k) \
;         acc[ai][bj][m][n] = __builtin_amdgcn_mfma_f32_16x16x32_bf16(Bt[n][k], At[m][k], acc[ai][bj][m][n], 0, 0, 0); __builtin_amdgcn_s_setprio(0); } while (0)
; #define PG8_WAIT_V(n) asm volatile("s_waitcnt vmcnt(" #n ")" ::: "memory")
; #define PG8_BAR __builtin_amdgcn_s_barrier()
;     __device__ __forceinline__ void operator()(const f32x4 (&acc)[2][2][4][2], const Unit& u, int wr, int wc, int fr, int fq) const {
;         const int row0 = u.pm * BM + wr * 64 + fr; const size_t col0 = (size_t)u.pn * BM + wc * 32 + 8 * fq;
; #pragma unroll
;         for (int ai = 0; ai < 2; ++ai)
; #pragma unroll
;             for (int m = 0; m < 4; ++m) { const size_t off = (size_t)(row0 + ai * HALF + m * 16) * 1024 + col0;
; #pragma unroll
;                 for (int bj = 0; bj < 2; ++bj) { const u32x4 gw = *(const u32x4*)(Gt + off + bj * HALF);
;                     f32x4 v0 = acc[ai][bj][m][0], v1 = acc[ai][bj][m][1];
;                     v0[0] *= bflo(gw.x); v0[1] *= bfhi(gw.x); v0[2] *= bflo(gw.y); v0[3] *= bfhi(gw.y);
;                     v1[0] *= bflo(gw.z); v1[1] *= bfhi(gw.z); v1[2] *= bflo(gw.w); v1[3] *= bfhi(gw.w);
;                     if (ADD) { const u32x4 pw = *(const u32x4*)(MG + off + bj * HALF);
; template <class Epi, class Sched, bool ALIGN_EPI = false, bool SP2 = false>
; __device__ __forceinline__ void gemm_phase(PG8_LAS unsigned char* lds, const Gemm g, const Sched& S, const Epi& E) {
;     ...
;             PG8_LDA(At, 1, 1); PG8_STAGE(PG8_SB(1, 0), b3, voffB); PG8_STAGE(PG8_SB(1, 1), b3 + hstep, voffB); PG8_STAGE(PG8_SA(1, 0), a3, voffA);
;             PG8_WAIT_V(8); PG8_WAIT_L(0); PG8_BAR; PG8_MMA(1, 0, At, B0); PG8_MMA(1, 1, At, B1); PG8_BAR; PG8_SCHED;
	s_add_i32 s22, s40, s27
	v_lshl_add_u64 v[144:145], v[144:145], 0, s[44:45]
	s_mov_b32 m0, s22
	ds_read_b128 v[178:181], v148 offset:49152
	ds_read_b128 v[182:185], v148 offset:50176
	ds_read_b128 v[194:197], v148 offset:51200
	ds_read_b128 v[198:201], v148 offset:52224
	ds_read_b128 v[202:205], v148 offset:53248
	ds_read_b128 v[210:213], v148 offset:54272
	ds_read_b128 v[214:217], v148 offset:55296
	ds_read_b128 v[218:221], v148 offset:56320
	global_load_lds_dwordx4 v[144:145], off
	s_add_i32 m0, s22, 0x2000
	s_add_u32 s20, s20, 0x40080
	v_lshl_add_u64 v[144:145], v[186:187], 0, s[44:45]
	s_addc_u32 s21, s21, 0
	s_add_i32 s22, s41, s27
	global_load_lds_dwordx4 v[144:145], off
	v_lshl_add_u64 v[144:145], s[20:21], 0, v[188:189]
	s_mov_b32 m0, s22
	s_nop 0
	global_load_lds_dwordx4 v[144:145], off
	v_lshl_add_u64 v[144:145], s[20:21], 0, v[132:133]
	s_add_i32 m0, s22, 0x2000
	s_nop 0
	global_load_lds_dwordx4 v[144:145], off
	v_lshl_add_u64 v[144:145], v[190:191], 0, s[44:45]
	s_mov_b32 m0, s34
	s_nop 0
	global_load_lds_dwordx4 v[144:145], off
	v_lshl_add_u64 v[144:145], v[222:223], 0, s[44:45]
	s_mov_b32 m0, s35
	s_nop 0
	global_load_lds_dwordx4 v[144:145], off
	s_waitcnt vmcnt(8)
	s_waitcnt lgkmcnt(0)
	s_barrier
	s_setprio 1
	s_waitcnt lgkmcnt(0)
	v_mfma_f32_16x16x32_bf16 v[60:63], v[140:143], v[178:181], v[60:63]
	v_mfma_f32_16x16x32_bf16 v[56:59], v[154:157], v[178:181], v[56:59]
	v_mfma_f32_16x16x32_bf16 v[44:47], v[140:143], v[194:197], v[44:47]
	v_mfma_f32_16x16x32_bf16 v[40:43], v[154:157], v[194:197], v[40:43]
	v_mfma_f32_16x16x32_bf16 v[28:31], v[140:143], v[202:205], v[28:31]
	v_mfma_f32_16x16x32_bf16 v[24:27], v[154:157], v[202:205], v[24:27]
	v_mfma_f32_16x16x32_bf16 v[12:15], v[140:143], v[214:217], v[12:15]
	v_mfma_f32_16x16x32_bf16 v[8:11], v[154:157], v[214:217], v[8:11]
	v_mfma_f32_16x16x32_bf16 v[60:63], v[150:153], v[182:185], v[60:63]
	v_mfma_f32_16x16x32_bf16 v[56:59], v[158:161], v[182:185], v[56:59]
	v_mfma_f32_16x16x32_bf16 v[44:47], v[150:153], v[198:201], v[44:47]
	v_mfma_f32_16x16x32_bf16 v[40:43], v[158:161], v[198:201], v[40:43]
	v_mfma_f32_16x16x32_bf16 v[28:31], v[150:153], v[210:213], v[28:31]
	v_mfma_f32_16x16x32_bf16 v[24:27], v[158:161], v[210:213], v[24:27]
	v_mfma_f32_16x16x32_bf16 v[12:15], v[150:153], v[218:221], v[12:15]
	v_mfma_f32_16x16x32_bf16 v[8:11], v[158:161], v[218:221], v[8:11]
	s_setprio 0
	s_setprio 1
	v_mfma_f32_16x16x32_bf16 v[52:55], v[162:165], v[178:181], v[52:55]
	v_mfma_f32_16x16x32_bf16 v[48:51], v[170:173], v[178:181], v[48:51]
	v_mfma_f32_16x16x32_bf16 v[36:39], v[162:165], v[194:197], v[36:39]
	v_mfma_f32_16x16x32_bf16 v[32:35], v[170:173], v[194:197], v[32:35]
	v_mfma_f32_16x16x32_bf16 v[20:23], v[162:165], v[202:205], v[20:23]
	v_mfma_f32_16x16x32_bf16 v[16:19], v[170:173], v[202:205], v[16:19]
	v_mfma_f32_16x16x32_bf16 v[4:7], v[162:165], v[214:217], v[4:7]
	v_mfma_f32_16x16x32_bf16 v[0:3], v[170:173], v[214:217], v[0:3]
	v_mfma_f32_16x16x32_bf16 v[52:55], v[166:169], v[182:185], v[52:55]
	v_mfma_f32_16x16x32_bf16 v[48:51], v[174:177], v[182:185], v[48:51]
	v_mfma_f32_16x16x32_bf16 v[36:39], v[166:169], v[198:201], v[36:39]
	v_mfma_f32_16x16x32_bf16 v[32:35], v[174:177], v[198:201], v[32:35]
	v_mfma_f32_16x16x32_bf16 v[20:23], v[166:169], v[210:213], v[20:23]
	v_mfma_f32_16x16x32_bf16 v[16:19], v[174:177], v[210:213], v[16:19]
	v_mfma_f32_16x16x32_bf16 v[4:7], v[166:169], v[218:221], v[4:7]
	v_mfma_f32_16x16x32_bf16 v[0:3], v[174:177], v[218:221], v[0:3]
	s_setprio 0
	s_barrier
	s_add_i32 s39, s39, 2
	s_add_u32 s18, s18, 0x100
	s_addc_u32 s19, s19, 0
	s_add_u32 s33, s33, 0x100
	s_addc_u32 s38, s38, 0
	s_cmp_gt_u32 s39, 13
	s_cbranch_scc0 .LBB0_725
	v_lshl_add_u32 v144, s14, 8, v146
	s_lshl_b32 s18, s16, 8
	v_or_b32_e32 v145, s18, v134
	v_lshlrev_b32_e32 v144, 11, v144
	v_lshl_add_u32 v144, v145, 1, v144
	v_readlane_b32 s16, v254, 44
	v_readlane_b32 s17, v254, 45
	v_readlane_b32 s14, v254, 21
	v_readlane_b32 s15, v254, 22
	s_mov_b64 s[18:19], s[16:17]
	s_mov_b64 s[38:39], s[14:15]
	global_load_dwordx4 v[140:143], v144, s[18:19]
	global_load_dwordx4 v[150:153], v144, s[38:39]
	global_load_dwordx4 v[154:157], v144, s[18:19] offset:256
	global_load_dwordx4 v[158:161], v144, s[38:39] offset:256
	s_add_u32 s18, s16, 0x8000
	s_addc_u32 s19, s17, 0
	s_add_u32 s38, s14, 0x8000
	s_addc_u32 s39, s15, 0
	global_load_dwordx4 v[162:165], v144, s[18:19]
	global_load_dwordx4 v[166:169], v144, s[38:39]
	global_load_dwordx4 v[170:173], v144, s[18:19] offset:256
	global_load_dwordx4 v[174:177], v144, s[38:39] offset:256
	s_add_u32 s18, s16, 0x10000
	s_addc_u32 s19, s17, 0
	s_add_u32 s38, s14, 0x10000
	s_addc_u32 s39, s15, 0
	global_load_dwordx4 v[178:181], v144, s[18:19]
	global_load_dwordx4 v[182:185], v144, s[38:39]
	global_load_dwordx4 v[194:197], v144, s[18:19] offset:256
	global_load_dwordx4 v[198:201], v144, s[38:39] offset:256
	s_add_u32 s18, s16, 0x18000
	s_addc_u32 s19, s17, 0
	s_add_u32 s38, s14, 0x18000
	s_addc_u32 s39, s15, 0
	global_load_dwordx4 v[202:205], v144, s[18:19]
	global_load_dwordx4 v[210:213], v144, s[38:39]
	global_load_dwordx4 v[214:217], v144, s[18:19] offset:256
	global_load_dwordx4 v[218:221], v144, s[38:39] offset:256
	s_and_b64 vcc, exec, s[2:3]
	s_cbranch_vccz .LBB0_728
	s_barrier
; __device__ __forceinline__ u32x4 pack8(const f32x4 a, const f32x4 b) { u32x4 w; w.x = cvt_pk_bf16(a[0], a[1]); w.y = cvt_pk_bf16(a[2], a[3]); w.z = cvt_pk_bf16(b[0], b[1]); w.w = cvt_pk_bf16(b[2], b[3]); return w; }
;     __device__ __forceinline__ void operator()(const f32x4 (&acc)[2][2][4][2], const Unit& u, int wr, int wc, int fr, int fq) const {
;     ...
;             for (int m = 0; m < 4; ++m) { const size_t off = (size_t)(row0 + ai * HALF + m * 16) * 1024 + col0;
; #pragma unroll
;                 for (int bj = 0; bj < 2; ++bj) { const u32x4 gw = *(const u32x4*)(Gt + off + bj * HALF);
;                     f32x4 v0 = acc[ai][bj][m][0], v1 = acc[ai][bj][m][1];
;                     v0[0] *= bflo(gw.x); v0[1] *= bfhi(gw.x); v0[2] *= bflo(gw.y); v0[3] *= bfhi(gw.y);
;                     v1[0] *= bflo(gw.z); v1[1] *= bfhi(gw.z); v1[2] *= bflo(gw.w); v1[3] *= bfhi(gw.w);
;                     if (ADD) { const u32x4 pw = *(const u32x4*)(MG + off + bj * HALF);
;                         v0[0] += bflo(pw.x); v0[1] += bfhi(pw.x); v0[2] += bflo(pw.y); v0[3] += bfhi(pw.y);
;                         v1[0] += bflo(pw.z); v1[1] += bfhi(pw.z); v1[2] += bflo(pw.w); v1[3] += bfhi(pw.w); }
;                     *(u32x4*)(MG + off + bj * HALF) = pack8(v0, v1); }
;                 asm volatile("" ::: "memory"); }
.LBB0_728:
	s_mov_b64 s[18:19], s[16:17]
	s_mov_b64 s[38:39], s[14:15]
	s_waitcnt vmcnt(14)
	v_lshlrev_b32_e32 v145, 16, v140
	v_lshlrev_b32_e32 v149, 16, v150
	v_and_b32_e32 v140, 0xffff0000, v140
	v_and_b32_e32 v150, 0xffff0000, v150
	v_fmac_f32_e32 v149, v124, v145
	v_fmac_f32_e32 v150, v125, v140
	v_cvt_pk_bf16_f32 v140, v149, v150
	v_lshlrev_b32_e32 v145, 16, v141
	v_lshlrev_b32_e32 v149, 16, v151
	v_and_b32_e32 v141, 0xffff0000, v141
	v_and_b32_e32 v151, 0xffff0000, v151
	v_fmac_f32_e32 v149, v126, v145
	v_fmac_f32_e32 v151, v127, v141
	v_cvt_pk_bf16_f32 v141, v149, v151
	v_lshlrev_b32_e32 v145, 16, v142
	v_lshlrev_b32_e32 v149, 16, v152
	v_and_b32_e32 v142, 0xffff0000, v142
	v_and_b32_e32 v152, 0xffff0000, v152
	v_fmac_f32_e32 v149, v120, v145
	v_fmac_f32_e32 v152, v121, v142
	v_cvt_pk_bf16_f32 v142, v149, v152
	v_lshlrev_b32_e32 v145, 16, v143
	v_lshlrev_b32_e32 v149, 16, v153
	v_and_b32_e32 v143, 0xffff0000, v143
	v_and_b32_e32 v153, 0xffff0000, v153
	v_fmac_f32_e32 v149, v122, v145
	v_fmac_f32_e32 v153, v123, v143
	v_cvt_pk_bf16_f32 v143, v149, v153
	global_store_dwordx4 v144, v[140:143], s[38:39]
	v_add_u32_e32 v145, 0x40000, v144
	global_load_dwordx4 v[150:153], v145, s[38:39]
	global_load_dwordx4 v[140:143], v145, s[18:19]
	s_waitcnt vmcnt(15)
	v_lshlrev_b32_e32 v145, 16, v154
	v_lshlrev_b32_e32 v149, 16, v158
	v_and_b32_e32 v154, 0xffff0000, v154
	v_and_b32_e32 v158, 0xffff0000, v158
	v_fmac_f32_e32 v149, v116, v145
	v_fmac_f32_e32 v158, v117, v154
	v_cvt_pk_bf16_f32 v154, v149, v158
	v_lshlrev_b32_e32 v145, 16, v155
	v_lshlrev_b32_e32 v149, 16, v159
	v_and_b32_e32 v155, 0xffff0000, v155
	v_and_b32_e32 v159, 0xffff0000, v159
	v_fmac_f32_e32 v149, v118, v145
	v_fmac_f32_e32 v159, v119, v155
	v_cvt_pk_bf16_f32 v155, v149, v159
	v_lshlrev_b32_e32 v145, 16, v156
	v_lshlrev_b32_e32 v149, 16, v160
	v_and_b32_e32 v156, 0xffff0000, v156
	v_and_b32_e32 v160, 0xffff0000, v160
	v_fmac_f32_e32 v149, v112, v145
	v_fmac_f32_e32 v160, v113, v156
	v_cvt_pk_bf16_f32 v156, v149, v160
	v_lshlrev_b32_e32 v145, 16, v157
	v_lshlrev_b32_e32 v149, 16, v161
	v_and_b32_e32 v157, 0xffff0000, v157
	v_and_b32_e32 v161, 0xffff0000, v161
	v_fmac_f32_e32 v149, v114, v145
	v_fmac_f32_e32 v161, v115, v157
	v_cvt_pk_bf16_f32 v157, v149, v161
	global_store_dwordx4 v144, v[154:157], s[38:39] offset:256
	v_add_u32_e32 v145, 0x40000, v144
	global_load_dwordx4 v[158:161], v145, s[38:39] offset:256
	global_load_dwordx4 v[154:157], v145, s[18:19] offset:256
	s_add_u32 s18, s16, 0x8000
	s_addc_u32 s19, s17, 0
	s_add_u32 s38, s14, 0x8000
	s_addc_u32 s39, s15, 0
	s_waitcnt vmcnt(16)
	v_lshlrev_b32_e32 v145, 16, v162
	v_lshlrev_b32_e32 v149, 16, v166
	v_and_b32_e32 v162, 0xffff0000, v162
	v_and_b32_e32 v166, 0xffff0000, v166
	v_fmac_f32_e32 v149, v108, v145
	v_fmac_f32_e32 v166, v109, v162
	v_cvt_pk_bf16_f32 v162, v149, v166
	v_lshlrev_b32_e32 v145, 16, v163
	v_lshlrev_b32_e32 v149, 16, v167
	v_and_b32_e32 v163, 0xffff0000, v163
	v_and_b32_e32 v167, 0xffff0000, v167
	v_fmac_f32_e32 v149, v110, v145
	v_fmac_f32_e32 v167, v111, v163
	v_cvt_pk_bf16_f32 v163, v149, v167
	v_lshlrev_b32_e32 v145, 16, v164
	v_lshlrev_b32_e32 v149, 16, v168
	v_and_b32_e32 v164, 0xffff0000, v164
	v_and_b32_e32 v168, 0xffff0000, v168
	v_fmac_f32_e32 v149, v104, v145
	v_fmac_f32_e32 v168, v105, v164
	v_cvt_pk_bf16_f32 v164, v149, v168
	v_lshlrev_b32_e32 v145, 16, v165
	v_lshlrev_b32_e32 v149, 16, v169
	v_and_b32_e32 v165, 0xffff0000, v165
	v_and_b32_e32 v169, 0xffff0000, v169
	v_fmac_f32_e32 v149, v106, v145
	v_fmac_f32_e32 v169, v107, v165
	v_cvt_pk_bf16_f32 v165, v149, v169
	global_store_dwordx4 v144, v[162:165], s[38:39]
	v_add_u32_e32 v145, 0x40000, v144
	global_load_dwordx4 v[166:169], v145, s[38:39]
	global_load_dwordx4 v[162:165], v145, s[18:19]
	s_waitcnt vmcnt(17)
	v_lshlrev_b32_e32 v145, 16, v170
	v_lshlrev_b32_e32 v149, 16, v174
	v_and_b32_e32 v170, 0xffff0000, v170
	v_and_b32_e32 v174, 0xffff0000, v174
	v_fmac_f32_e32 v149, v100, v145
	v_fmac_f32_e32 v174, v101, v170
	v_cvt_pk_bf16_f32 v170, v149, v174
	v_lshlrev_b32_e32 v145, 16, v171
	v_lshlrev_b32_e32 v149, 16, v175
	v_and_b32_e32 v171, 0xffff0000, v171
	v_and_b32_e32 v175, 0xffff0000, v175
	v_fmac_f32_e32 v149, v102, v145
	v_fmac_f32_e32 v175, v103, v171
	v_cvt_pk_bf16_f32 v171, v149, v175
	v_lshlrev_b32_e32 v145, 16, v172
	v_lshlrev_b32_e32 v149, 16, v176
	v_and_b32_e32 v172, 0xffff0000, v172
	v_and_b32_e32 v176, 0xffff0000, v176
	v_fmac_f32_e32 v149, v96, v145
	v_fmac_f32_e32 v176, v97, v172
	v_cvt_pk_bf16_f32 v172, v149, v176
	v_lshlrev_b32_e32 v145, 16, v173
	v_lshlrev_b32_e32 v149, 16, v177
	v_and_b32_e32 v173, 0xffff0000, v173
	v_and_b32_e32 v177, 0xffff0000, v177
	v_fmac_f32_e32 v149, v98, v145
	v_fmac_f32_e32 v177, v99, v173
	v_cvt_pk_bf16_f32 v173, v149, v177
	global_store_dwordx4 v144, v[170:173], s[38:39] offset:256
	v_add_u32_e32 v145, 0x40000, v144
	global_load_dwordx4 v[174:177], v145, s[38:39] offset:256
	global_load_dwordx4 v[170:173], v145, s[18:19] offset:256
	s_add_u32 s18, s16, 0x10000
	s_addc_u32 s19, s17, 0
	s_add_u32 s38, s14, 0x10000
	s_addc_u32 s39, s15, 0
	s_waitcnt vmcnt(18)
; __device__ __forceinline__ u32x4 pack8(const f32x4 a, const f32x4 b) { u32x4 w; w.x = cvt_pk_bf16(a[0], a[1]); w.y = cvt_pk_bf16(a[2], a[3]); w.z = cvt_pk_bf16(b[0], b[1]); w.w = cvt_pk_bf16(b[2], b[3]); return w; }
;     __device__ __forceinline__ void operator()(const f32x4 (&acc)[2][2][4][2], const Unit& u, int wr, int wc, int fr, int fq) const {
;     ...
;             for (int m = 0; m < 4; ++m) { const size_t off = (size_t)(row0 + ai * HALF + m * 16) * 1024 + col0;
; #pragma unroll
;                 for (int bj = 0; bj < 2; ++bj) { const u32x4 gw = *(const u32x4*)(Gt + off + bj * HALF);
;                     f32x4 v0 = acc[ai][bj][m][0], v1 = acc[ai][bj][m][1];
;                     v0[0] *= bflo(gw.x); v0[1] *= bfhi(gw.x); v0[2] *= bflo(gw.y); v0[3] *= bfhi(gw.y);
;                     v1[0] *= bflo(gw.z); v1[1] *= bfhi(gw.z); v1[2] *= bflo(gw.w); v1[3] *= bfhi(gw.w);
;                     if (ADD) { const u32x4 pw = *(const u32x4*)(MG + off + bj * HALF);
;                         v0[0] += bflo(pw.x); v0[1] += bfhi(pw.x); v0[2] += bflo(pw.y); v0[3] += bfhi(pw.y);
;                         v1[0] += bflo(pw.z); v1[1] += bfhi(pw.z); v1[2] += bflo(pw.w); v1[3] += bfhi(pw.w); }
;                     *(u32x4*)(MG + off + bj * HALF) = pack8(v0, v1); }
;                 asm volatile("" ::: "memory"); }
	v_lshlrev_b32_e32 v145, 16, v178
	v_lshlrev_b32_e32 v149, 16, v182
	v_and_b32_e32 v178, 0xffff0000, v178
	v_and_b32_e32 v182, 0xffff0000, v182
	v_fmac_f32_e32 v149, v92, v145
	v_fmac_f32_e32 v182, v93, v178
	v_cvt_pk_bf16_f32 v178, v149, v182
	v_lshlrev_b32_e32 v145, 16, v179
	v_lshlrev_b32_e32 v149, 16, v183
	v_and_b32_e32 v179, 0xffff0000, v179
	v_and_b32_e32 v183, 0xffff0000, v183
	v_fmac_f32_e32 v149, v94, v145
	v_fmac_f32_e32 v183, v95, v179
	v_cvt_pk_bf16_f32 v179, v149, v183
	v_lshlrev_b32_e32 v145, 16, v180
	v_lshlrev_b32_e32 v149, 16, v184
	v_and_b32_e32 v180, 0xffff0000, v180
	v_and_b32_e32 v184, 0xffff0000, v184
	v_fmac_f32_e32 v149, v88, v145
	v_fmac_f32_e32 v184, v89, v180
	v_cvt_pk_bf16_f32 v180, v149, v184
	v_lshlrev_b32_e32 v145, 16, v181
	v_lshlrev_b32_e32 v149, 16, v185
	v_and_b32_e32 v181, 0xffff0000, v181
	v_and_b32_e32 v185, 0xffff0000, v185
	v_fmac_f32_e32 v149, v90, v145
	v_fmac_f32_e32 v185, v91, v181
	v_cvt_pk_bf16_f32 v181, v149, v185
	global_store_dwordx4 v144, v[178:181], s[38:39]
	v_add_u32_e32 v145, 0x40000, v144
	global_load_dwordx4 v[182:185], v145, s[38:39]
	global_load_dwordx4 v[178:181], v145, s[18:19]
	s_waitcnt vmcnt(19)
	v_lshlrev_b32_e32 v145, 16, v194
	v_lshlrev_b32_e32 v149, 16, v198
	v_and_b32_e32 v194, 0xffff0000, v194
	v_and_b32_e32 v198, 0xffff0000, v198
	v_fmac_f32_e32 v149, v84, v145
	v_fmac_f32_e32 v198, v85, v194
	v_cvt_pk_bf16_f32 v194, v149, v198
	v_lshlrev_b32_e32 v145, 16, v195
	v_lshlrev_b32_e32 v149, 16, v199
	v_and_b32_e32 v195, 0xffff0000, v195
	v_and_b32_e32 v199, 0xffff0000, v199
	v_fmac_f32_e32 v149, v86, v145
	v_fmac_f32_e32 v199, v87, v195
	v_cvt_pk_bf16_f32 v195, v149, v199
	v_lshlrev_b32_e32 v145, 16, v196
	v_lshlrev_b32_e32 v149, 16, v200
	v_and_b32_e32 v196, 0xffff0000, v196
	v_and_b32_e32 v200, 0xffff0000, v200
	v_fmac_f32_e32 v149, v80, v145
	v_fmac_f32_e32 v200, v81, v196
	v_cvt_pk_bf16_f32 v196, v149, v200
	v_lshlrev_b32_e32 v145, 16, v197
	v_lshlrev_b32_e32 v149, 16, v201
	v_and_b32_e32 v197, 0xffff0000, v197
	v_and_b32_e32 v201, 0xffff0000, v201
	v_fmac_f32_e32 v149, v82, v145
	v_fmac_f32_e32 v201, v83, v197
	v_cvt_pk_bf16_f32 v197, v149, v201
	global_store_dwordx4 v144, v[194:197], s[38:39] offset:256
	v_add_u32_e32 v145, 0x40000, v144
	global_load_dwordx4 v[198:201], v145, s[38:39] offset:256
	global_load_dwordx4 v[194:197], v145, s[18:19] offset:256
	s_add_u32 s18, s16, 0x18000
	s_addc_u32 s19, s17, 0
	s_add_u32 s38, s14, 0x18000
	s_addc_u32 s39, s15, 0
	s_waitcnt vmcnt(20)
	v_lshlrev_b32_e32 v145, 16, v202
	v_lshlrev_b32_e32 v149, 16, v210
	v_and_b32_e32 v202, 0xffff0000, v202
	v_and_b32_e32 v210, 0xffff0000, v210
	v_fmac_f32_e32 v149, v76, v145
	v_fmac_f32_e32 v210, v77, v202
	v_cvt_pk_bf16_f32 v202, v149, v210
	v_lshlrev_b32_e32 v145, 16, v203
	v_lshlrev_b32_e32 v149, 16, v211
	v_and_b32_e32 v203, 0xffff0000, v203
	v_and_b32_e32 v211, 0xffff0000, v211
	v_fmac_f32_e32 v149, v78, v145
	v_fmac_f32_e32 v211, v79, v203
	v_cvt_pk_bf16_f32 v203, v149, v211
	v_lshlrev_b32_e32 v145, 16, v204
	v_lshlrev_b32_e32 v149, 16, v212
	v_and_b32_e32 v204, 0xffff0000, v204
	v_and_b32_e32 v212, 0xffff0000, v212
	v_fmac_f32_e32 v149, v72, v145
	v_fmac_f32_e32 v212, v73, v204
	v_cvt_pk_bf16_f32 v204, v149, v212
	v_lshlrev_b32_e32 v145, 16, v205
	v_lshlrev_b32_e32 v149, 16, v213
	v_and_b32_e32 v205, 0xffff0000, v205
	v_and_b32_e32 v213, 0xffff0000, v213
	v_fmac_f32_e32 v149, v74, v145
	v_fmac_f32_e32 v213, v75, v205
	v_cvt_pk_bf16_f32 v205, v149, v213
	global_store_dwordx4 v144, v[202:205], s[38:39]
	v_add_u32_e32 v145, 0x40000, v144
	global_load_dwordx4 v[210:213], v145, s[38:39]
	global_load_dwordx4 v[202:205], v145, s[18:19]
	s_waitcnt vmcnt(21)
	v_lshlrev_b32_e32 v145, 16, v214
	v_lshlrev_b32_e32 v149, 16, v218
	v_and_b32_e32 v214, 0xffff0000, v214
	v_and_b32_e32 v218, 0xffff0000, v218
	v_fmac_f32_e32 v149, v68, v145
	v_fmac_f32_e32 v218, v69, v214
	v_cvt_pk_bf16_f32 v214, v149, v218
	v_lshlrev_b32_e32 v145, 16, v215
	v_lshlrev_b32_e32 v149, 16, v219
	v_and_b32_e32 v215, 0xffff0000, v215
	v_and_b32_e32 v219, 0xffff0000, v219
	v_fmac_f32_e32 v149, v70, v145
	v_fmac_f32_e32 v219, v71, v215
	v_cvt_pk_bf16_f32 v215, v149, v219
	v_lshlrev_b32_e32 v145, 16, v216
	v_lshlrev_b32_e32 v149, 16, v220
	v_and_b32_e32 v216, 0xffff0000, v216
	v_and_b32_e32 v220, 0xffff0000, v220
	v_fmac_f32_e32 v149, v64, v145
	v_fmac_f32_e32 v220, v65, v216
	v_cvt_pk_bf16_f32 v216, v149, v220
	v_lshlrev_b32_e32 v145, 16, v217
	v_lshlrev_b32_e32 v149, 16, v221
	v_and_b32_e32 v217, 0xffff0000, v217
	v_and_b32_e32 v221, 0xffff0000, v221
	v_fmac_f32_e32 v149, v66, v145
	v_fmac_f32_e32 v221, v67, v217
	v_cvt_pk_bf16_f32 v217, v149, v221
	global_store_dwordx4 v144, v[214:217], s[38:39] offset:256
	v_add_u32_e32 v145, 0x40000, v144
	global_load_dwordx4 v[218:221], v145, s[38:39] offset:256
	global_load_dwordx4 v[214:217], v145, s[18:19] offset:256
	s_mov_b64 s[18:19], s[16:17]
	s_mov_b64 s[38:39], s[14:15]
	s_waitcnt vmcnt(21)
	v_lshlrev_b32_e32 v145, 16, v140
	v_lshlrev_b32_e32 v149, 16, v150
	v_and_b32_e32 v140, 0xffff0000, v140
	v_and_b32_e32 v150, 0xffff0000, v150
	v_fmac_f32_e32 v149, v60, v145
	v_fmac_f32_e32 v150, v61, v140
	v_cvt_pk_bf16_f32 v140, v149, v150
	v_lshlrev_b32_e32 v145, 16, v141
	v_lshlrev_b32_e32 v149, 16, v151
	v_and_b32_e32 v141, 0xffff0000, v141
	v_and_b32_e32 v151, 0xffff0000, v151
	v_fmac_f32_e32 v149, v62, v145
	v_fmac_f32_e32 v151, v63, v141
	v_cvt_pk_bf16_f32 v141, v149, v151
	v_lshlrev_b32_e32 v145, 16, v142
	v_lshlrev_b32_e32 v149, 16, v152
	v_and_b32_e32 v142, 0xffff0000, v142
	v_and_b32_e32 v152, 0xffff0000, v152
	v_fmac_f32_e32 v149, v56, v145
	v_fmac_f32_e32 v152, v57, v142
	v_cvt_pk_bf16_f32 v142, v149, v152
	v_lshlrev_b32_e32 v145, 16, v143
	v_lshlrev_b32_e32 v149, 16, v153
	v_and_b32_e32 v143, 0xffff0000, v143
	v_and_b32_e32 v153, 0xffff0000, v153
	v_fmac_f32_e32 v149, v58, v145
	v_fmac_f32_e32 v153, v59, v143
	v_cvt_pk_bf16_f32 v143, v149, v153
	v_add_u32_e32 v145, 0x40000, v144
	global_store_dwordx4 v145, v[140:143], s[38:39]
	s_waitcnt vmcnt(19)
; __device__ __forceinline__ u32x4 pack8(const f32x4 a, const f32x4 b) { u32x4 w; w.x = cvt_pk_bf16(a[0], a[1]); w.y = cvt_pk_bf16(a[2], a[3]); w.z = cvt_pk_bf16(b[0], b[1]); w.w = cvt_pk_bf16(b[2], b[3]); return w; }
;     __device__ __forceinline__ void operator()(const f32x4 (&acc)[2][2][4][2], const Unit& u, int wr, int wc, int fr, int fq) const {
;     ...
;             for (int m = 0; m < 4; ++m) { const size_t off = (size_t)(row0 + ai * HALF + m * 16) * 1024 + col0;
; #pragma unroll
;                 for (int bj = 0; bj < 2; ++bj) { const u32x4 gw = *(const u32x4*)(Gt + off + bj * HALF);
;                     f32x4 v0 = acc[ai][bj][m][0], v1 = acc[ai][bj][m][1];
;                     v0[0] *= bflo(gw.x); v0[1] *= bfhi(gw.x); v0[2] *= bflo(gw.y); v0[3] *= bfhi(gw.y);
;                     v1[0] *= bflo(gw.z); v1[1] *= bfhi(gw.z); v1[2] *= bflo(gw.w); v1[3] *= bfhi(gw.w);
;                     if (ADD) { const u32x4 pw = *(const u32x4*)(MG + off + bj * HALF);
;                         v0[0] += bflo(pw.x); v0[1] += bfhi(pw.x); v0[2] += bflo(pw.y); v0[3] += bfhi(pw.y);
;                         v1[0] += bflo(pw.z); v1[1] += bfhi(pw.z); v1[2] += bflo(pw.w); v1[3] += bfhi(pw.w); }
;                     *(u32x4*)(MG + off + bj * HALF) = pack8(v0, v1); }
;                 asm volatile("" ::: "memory"); }
	v_lshlrev_b32_e32 v145, 16, v154
	v_lshlrev_b32_e32 v149, 16, v158
	v_and_b32_e32 v154, 0xffff0000, v154
	v_and_b32_e32 v158, 0xffff0000, v158
	v_fmac_f32_e32 v149, v52, v145
	v_fmac_f32_e32 v158, v53, v154
	v_cvt_pk_bf16_f32 v154, v149, v158
	v_lshlrev_b32_e32 v145, 16, v155
	v_lshlrev_b32_e32 v149, 16, v159
	v_and_b32_e32 v155, 0xffff0000, v155
	v_and_b32_e32 v159, 0xffff0000, v159
	v_fmac_f32_e32 v149, v54, v145
	v_fmac_f32_e32 v159, v55, v155
	v_cvt_pk_bf16_f32 v155, v149, v159
	v_lshlrev_b32_e32 v145, 16, v156
	v_lshlrev_b32_e32 v149, 16, v160
	v_and_b32_e32 v156, 0xffff0000, v156
	v_and_b32_e32 v160, 0xffff0000, v160
	v_fmac_f32_e32 v149, v48, v145
	v_fmac_f32_e32 v160, v49, v156
	v_cvt_pk_bf16_f32 v156, v149, v160
	v_lshlrev_b32_e32 v145, 16, v157
	v_lshlrev_b32_e32 v149, 16, v161
	v_and_b32_e32 v157, 0xffff0000, v157
	v_and_b32_e32 v161, 0xffff0000, v161
	v_fmac_f32_e32 v149, v50, v145
	v_fmac_f32_e32 v161, v51, v157
	v_cvt_pk_bf16_f32 v157, v149, v161
	v_add_u32_e32 v145, 0x40000, v144
	global_store_dwordx4 v145, v[154:157], s[38:39] offset:256
	s_add_u32 s18, s16, 0x8000
	s_addc_u32 s19, s17, 0
	s_add_u32 s38, s14, 0x8000
	s_addc_u32 s39, s15, 0
	s_waitcnt vmcnt(17)
	v_lshlrev_b32_e32 v145, 16, v162
	v_lshlrev_b32_e32 v149, 16, v166
	v_and_b32_e32 v162, 0xffff0000, v162
	v_and_b32_e32 v166, 0xffff0000, v166
	v_fmac_f32_e32 v149, v44, v145
	v_fmac_f32_e32 v166, v45, v162
	v_cvt_pk_bf16_f32 v162, v149, v166
	v_lshlrev_b32_e32 v145, 16, v163
	v_lshlrev_b32_e32 v149, 16, v167
	v_and_b32_e32 v163, 0xffff0000, v163
	v_and_b32_e32 v167, 0xffff0000, v167
	v_fmac_f32_e32 v149, v46, v145
	v_fmac_f32_e32 v167, v47, v163
	v_cvt_pk_bf16_f32 v163, v149, v167
	v_lshlrev_b32_e32 v145, 16, v164
	v_lshlrev_b32_e32 v149, 16, v168
	v_and_b32_e32 v164, 0xffff0000, v164
	v_and_b32_e32 v168, 0xffff0000, v168
	v_fmac_f32_e32 v149, v40, v145
	v_fmac_f32_e32 v168, v41, v164
	v_cvt_pk_bf16_f32 v164, v149, v168
	v_lshlrev_b32_e32 v145, 16, v165
	v_lshlrev_b32_e32 v149, 16, v169
	v_and_b32_e32 v165, 0xffff0000, v165
	v_and_b32_e32 v169, 0xffff0000, v169
	v_fmac_f32_e32 v149, v42, v145
	v_fmac_f32_e32 v169, v43, v165
	v_cvt_pk_bf16_f32 v165, v149, v169
	v_add_u32_e32 v145, 0x40000, v144
	global_store_dwordx4 v145, v[162:165], s[38:39]
	s_waitcnt vmcnt(15)
	v_lshlrev_b32_e32 v145, 16, v170
	v_lshlrev_b32_e32 v149, 16, v174
	v_and_b32_e32 v170, 0xffff0000, v170
	v_and_b32_e32 v174, 0xffff0000, v174
	v_fmac_f32_e32 v149, v36, v145
	v_fmac_f32_e32 v174, v37, v170
	v_cvt_pk_bf16_f32 v170, v149, v174
	v_lshlrev_b32_e32 v145, 16, v171
	v_lshlrev_b32_e32 v149, 16, v175
	v_and_b32_e32 v171, 0xffff0000, v171
	v_and_b32_e32 v175, 0xffff0000, v175
	v_fmac_f32_e32 v149, v38, v145
	v_fmac_f32_e32 v175, v39, v171
	v_cvt_pk_bf16_f32 v171, v149, v175
	v_lshlrev_b32_e32 v145, 16, v172
	v_lshlrev_b32_e32 v149, 16, v176
	v_and_b32_e32 v172, 0xffff0000, v172
	v_and_b32_e32 v176, 0xffff0000, v176
	v_fmac_f32_e32 v149, v32, v145
	v_fmac_f32_e32 v176, v33, v172
	v_cvt_pk_bf16_f32 v172, v149, v176
	v_lshlrev_b32_e32 v145, 16, v173
	v_lshlrev_b32_e32 v149, 16, v177
	v_and_b32_e32 v173, 0xffff0000, v173
	v_and_b32_e32 v177, 0xffff0000, v177
	v_fmac_f32_e32 v149, v34, v145
	v_fmac_f32_e32 v177, v35, v173
	v_cvt_pk_bf16_f32 v173, v149, v177
	v_add_u32_e32 v145, 0x40000, v144
	global_store_dwordx4 v145, v[170:173], s[38:39] offset:256
	s_add_u32 s18, s16, 0x10000
	s_addc_u32 s19, s17, 0
	s_add_u32 s38, s14, 0x10000
	s_addc_u32 s39, s15, 0
	s_waitcnt vmcnt(13)
	v_lshlrev_b32_e32 v145, 16, v178
	v_lshlrev_b32_e32 v149, 16, v182
	v_and_b32_e32 v178, 0xffff0000, v178
	v_and_b32_e32 v182, 0xffff0000, v182
	v_fmac_f32_e32 v149, v28, v145
	v_fmac_f32_e32 v182, v29, v178
	v_cvt_pk_bf16_f32 v178, v149, v182
	v_lshlrev_b32_e32 v145, 16, v179
	v_lshlrev_b32_e32 v149, 16, v183
	v_and_b32_e32 v179, 0xffff0000, v179
	v_and_b32_e32 v183, 0xffff0000, v183
	v_fmac_f32_e32 v149, v30, v145
	v_fmac_f32_e32 v183, v31, v179
	v_cvt_pk_bf16_f32 v179, v149, v183
	v_lshlrev_b32_e32 v145, 16, v180
	v_lshlrev_b32_e32 v149, 16, v184
	v_and_b32_e32 v180, 0xffff0000, v180
	v_and_b32_e32 v184, 0xffff0000, v184
	v_fmac_f32_e32 v149, v24, v145
	v_fmac_f32_e32 v184, v25, v180
	v_cvt_pk_bf16_f32 v180, v149, v184
	v_lshlrev_b32_e32 v145, 16, v181
	v_lshlrev_b32_e32 v149, 16, v185
	v_and_b32_e32 v181, 0xffff0000, v181
	v_and_b32_e32 v185, 0xffff0000, v185
	v_fmac_f32_e32 v149, v26, v145
	v_fmac_f32_e32 v185, v27, v181
	v_cvt_pk_bf16_f32 v181, v149, v185
	v_add_u32_e32 v145, 0x40000, v144
	global_store_dwordx4 v145, v[178:181], s[38:39]
	s_waitcnt vmcnt(11)
; __device__ __forceinline__ u32x4 pack8(const f32x4 a, const f32x4 b) { u32x4 w; w.x = cvt_pk_bf16(a[0], a[1]); w.y = cvt_pk_bf16(a[2], a[3]); w.z = cvt_pk_bf16(b[0], b[1]); w.w = cvt_pk_bf16(b[2], b[3]); return w; }
;     __device__ __forceinline__ void operator()(const f32x4 (&acc)[2][2][4][2], const Unit& u, int wr, int wc, int fr, int fq) const {
;     ...
;             for (int m = 0; m < 4; ++m) { const size_t off = (size_t)(row0 + ai * HALF + m * 16) * 1024 + col0;
; #pragma unroll
;                 for (int bj = 0; bj < 2; ++bj) { const u32x4 gw = *(const u32x4*)(Gt + off + bj * HALF);
;                     f32x4 v0 = acc[ai][bj][m][0], v1 = acc[ai][bj][m][1];
;                     v0[0] *= bflo(gw.x); v0[1] *= bfhi(gw.x); v0[2] *= bflo(gw.y); v0[3] *= bfhi(gw.y);
;                     v1[0] *= bflo(gw.z); v1[1] *= bfhi(gw.z); v1[2] *= bflo(gw.w); v1[3] *= bfhi(gw.w);
;                     if (ADD) { const u32x4 pw = *(const u32x4*)(MG + off + bj * HALF);
;                         v0[0] += bflo(pw.x); v0[1] += bfhi(pw.x); v0[2] += bflo(pw.y); v0[3] += bfhi(pw.y);
;                         v1[0] += bflo(pw.z); v1[1] += bfhi(pw.z); v1[2] += bflo(pw.w); v1[3] += bfhi(pw.w); }
;                     *(u32x4*)(MG + off + bj * HALF) = pack8(v0, v1); }
;                 asm volatile("" ::: "memory"); }
	v_lshlrev_b32_e32 v145, 16, v194
	v_lshlrev_b32_e32 v149, 16, v198
	v_and_b32_e32 v194, 0xffff0000, v194
	v_and_b32_e32 v198, 0xffff0000, v198
	v_fmac_f32_e32 v149, v20, v145
	v_fmac_f32_e32 v198, v21, v194
	v_cvt_pk_bf16_f32 v194, v149, v198
	v_lshlrev_b32_e32 v145, 16, v195
	v_lshlrev_b32_e32 v149, 16, v199
	v_and_b32_e32 v195, 0xffff0000, v195
	v_and_b32_e32 v199, 0xffff0000, v199
	v_fmac_f32_e32 v149, v22, v145
	v_fmac_f32_e32 v199, v23, v195
	v_cvt_pk_bf16_f32 v195, v149, v199
	v_lshlrev_b32_e32 v145, 16, v196
	v_lshlrev_b32_e32 v149, 16, v200
	v_and_b32_e32 v196, 0xffff0000, v196
	v_and_b32_e32 v200, 0xffff0000, v200
	v_fmac_f32_e32 v149, v16, v145
	v_fmac_f32_e32 v200, v17, v196
	v_cvt_pk_bf16_f32 v196, v149, v200
	v_lshlrev_b32_e32 v145, 16, v197
	v_lshlrev_b32_e32 v149, 16, v201
	v_and_b32_e32 v197, 0xffff0000, v197
	v_and_b32_e32 v201, 0xffff0000, v201
	v_fmac_f32_e32 v149, v18, v145
	v_fmac_f32_e32 v201, v19, v197
	v_cvt_pk_bf16_f32 v197, v149, v201
	v_add_u32_e32 v145, 0x40000, v144
	global_store_dwordx4 v145, v[194:197], s[38:39] offset:256
	s_add_u32 s18, s16, 0x18000
	s_addc_u32 s19, s17, 0
	s_add_u32 s38, s14, 0x18000
	s_addc_u32 s39, s15, 0
	s_waitcnt vmcnt(9)
	v_lshlrev_b32_e32 v145, 16, v202
	v_lshlrev_b32_e32 v149, 16, v210
	v_and_b32_e32 v202, 0xffff0000, v202
	v_and_b32_e32 v210, 0xffff0000, v210
	v_fmac_f32_e32 v149, v12, v145
	v_fmac_f32_e32 v210, v13, v202
	v_cvt_pk_bf16_f32 v202, v149, v210
	v_lshlrev_b32_e32 v145, 16, v203
	v_lshlrev_b32_e32 v149, 16, v211
	v_and_b32_e32 v203, 0xffff0000, v203
	v_and_b32_e32 v211, 0xffff0000, v211
	v_fmac_f32_e32 v149, v14, v145
	v_fmac_f32_e32 v211, v15, v203
	v_cvt_pk_bf16_f32 v203, v149, v211
	v_lshlrev_b32_e32 v145, 16, v204
	v_lshlrev_b32_e32 v149, 16, v212
	v_and_b32_e32 v204, 0xffff0000, v204
	v_and_b32_e32 v212, 0xffff0000, v212
	v_fmac_f32_e32 v149, v8, v145
	v_fmac_f32_e32 v212, v9, v204
	v_cvt_pk_bf16_f32 v204, v149, v212
	v_lshlrev_b32_e32 v145, 16, v205
	v_lshlrev_b32_e32 v149, 16, v213
	v_and_b32_e32 v205, 0xffff0000, v205
	v_and_b32_e32 v213, 0xffff0000, v213
	v_fmac_f32_e32 v149, v10, v145
	v_fmac_f32_e32 v213, v11, v205
	v_cvt_pk_bf16_f32 v205, v149, v213
	v_add_u32_e32 v145, 0x40000, v144
	global_store_dwordx4 v145, v[202:205], s[38:39]
	s_waitcnt vmcnt(7)
	v_lshlrev_b32_e32 v145, 16, v214
	v_lshlrev_b32_e32 v149, 16, v218
	v_and_b32_e32 v214, 0xffff0000, v214
	v_and_b32_e32 v218, 0xffff0000, v218
	v_fmac_f32_e32 v149, v4, v145
	v_fmac_f32_e32 v218, v5, v214
	v_cvt_pk_bf16_f32 v214, v149, v218
	v_lshlrev_b32_e32 v145, 16, v215
	v_lshlrev_b32_e32 v149, 16, v219
	v_and_b32_e32 v215, 0xffff0000, v215
	v_and_b32_e32 v219, 0xffff0000, v219
	v_fmac_f32_e32 v149, v6, v145
	v_fmac_f32_e32 v219, v7, v215
	v_cvt_pk_bf16_f32 v215, v149, v219
	v_lshlrev_b32_e32 v145, 16, v216
	v_lshlrev_b32_e32 v149, 16, v220
	v_and_b32_e32 v216, 0xffff0000, v216
	v_and_b32_e32 v220, 0xffff0000, v220
	v_fmac_f32_e32 v149, v0, v145
	v_fmac_f32_e32 v220, v1, v216
	v_cvt_pk_bf16_f32 v216, v149, v220
	v_lshlrev_b32_e32 v145, 16, v217
	v_lshlrev_b32_e32 v149, 16, v221
	v_and_b32_e32 v217, 0xffff0000, v217
	v_and_b32_e32 v221, 0xffff0000, v221
	v_fmac_f32_e32 v149, v2, v145
	v_fmac_f32_e32 v221, v3, v217
	v_cvt_pk_bf16_f32 v217, v149, v221
	v_add_u32_e32 v145, 0x40000, v144
	global_store_dwordx4 v145, v[214:217], s[38:39] offset:256
	s_mov_b64 s[14:15], -1
	v_readlane_b32 s16, v254, 44
	v_readlane_b32 s17, v254, 45
	s_mov_b64 s[18:19], 0x40000
	v_readlane_b32 s38, v254, 55
	v_readlane_b32 s39, v254, 56
	s_andn2_b64 vcc, exec, s[4:5]
	s_cbranch_vccnz .LBB0_719
	s_andn2_b64 vcc, exec, s[0:1]
	s_cbranch_vccnz .LBB0_718
	s_barrier
	s_branch .LBB0_718
